# grid barrier: early buffer_inv only (no pre-clean wbl2), to attribute the v044 gain
# baseline (speedup 1.0000x reference)
.LBB0_141:
	s_or_b64 exec, exec, s[8:9]
	v_cvt_f32_u32_e32 v4, v2
	s_waitcnt vmcnt(0)
	buffer_inv sc1
	v_readfirstlane_b32 s6, v3
	v_sub_u32_e32 v3, 0, v2
	v_rcp_iflag_f32_e32 v4, v4
	v_add_u32_e32 v5, s6, v1
	v_mul_f32_e32 v4, 0x4f7ffffe, v4
	v_cvt_u32_f32_e32 v4, v4
	v_mul_lo_u32 v1, v3, v4
	v_mul_hi_u32 v1, v4, v1
	v_add_u32_e32 v1, v4, v1
	v_mul_hi_u32 v1, v5, v1
	v_mul_lo_u32 v3, v1, v2
	v_sub_u32_e32 v3, v5, v3
	v_add_u32_e32 v4, 1, v1
	v_cmp_ge_u32_e32 vcc, v3, v2
	s_nop 1
	v_cndmask_b32_e32 v1, v1, v4, vcc
	v_sub_u32_e32 v4, v3, v2
	v_cndmask_b32_e32 v3, v3, v4, vcc
	v_add_u32_e32 v4, 1, v1
	v_cmp_ge_u32_e32 vcc, v3, v2
	v_add_u32_e32 v3, 1, v5
	s_nop 0
	v_cndmask_b32_e32 v1, v1, v4, vcc
	v_mul_lo_u32 v4, v2, v1
	v_add_u32_e32 v2, v4, v2
	v_cmp_ne_u32_e32 vcc, v3, v2
	s_and_saveexec_b64 s[6:7], vcc
	s_xor_b64 s[6:7], exec, s[6:7]
	s_cbranch_execz .LBB0_155
	s_waitcnt lgkmcnt(0)
	v_mov_b32_e32 v0, 0x2000
	global_load_dword v0, v0, s[4:5] offset:1024 sc1
	s_add_u32 s12, s4, 0x2400
	s_addc_u32 s13, s5, 0
	s_waitcnt vmcnt(0)
	v_cmp_eq_u32_e32 vcc, v0, v1
	s_and_saveexec_b64 s[8:9], vcc
	s_cbranch_execz .LBB0_154
	s_add_u32 s10, s40, 0x4200
	s_addc_u32 s11, s41, 0
	s_mov_b32 s44, 1
	s_mov_b64 s[18:19], 0
	v_mov_b32_e32 v0, 0
	s_branch .LBB0_145

.LBB0_209:
	s_or_b64 exec, exec, s[8:9]
	v_cvt_f32_u32_e32 v4, v2
	s_waitcnt vmcnt(0)
	buffer_inv sc1
	v_readfirstlane_b32 s6, v3
	v_sub_u32_e32 v3, 0, v2
	v_rcp_iflag_f32_e32 v4, v4
	v_add_u32_e32 v5, s6, v1
	v_mul_f32_e32 v4, 0x4f7ffffe, v4
	v_cvt_u32_f32_e32 v4, v4
	v_mul_lo_u32 v1, v3, v4
	v_mul_hi_u32 v1, v4, v1
	v_add_u32_e32 v1, v4, v1
	v_mul_hi_u32 v1, v5, v1
	v_mul_lo_u32 v3, v1, v2
	v_sub_u32_e32 v3, v5, v3
	v_add_u32_e32 v4, 1, v1
	v_cmp_ge_u32_e32 vcc, v3, v2
	s_nop 1
	v_cndmask_b32_e32 v1, v1, v4, vcc
	v_sub_u32_e32 v4, v3, v2
	v_cndmask_b32_e32 v3, v3, v4, vcc
	v_add_u32_e32 v4, 1, v1
	v_cmp_ge_u32_e32 vcc, v3, v2
	v_add_u32_e32 v3, 1, v5
	s_nop 0
	v_cndmask_b32_e32 v1, v1, v4, vcc
	v_mul_lo_u32 v4, v2, v1
	v_add_u32_e32 v2, v4, v2
	v_cmp_ne_u32_e32 vcc, v3, v2
	s_and_saveexec_b64 s[6:7], vcc
	s_xor_b64 s[6:7], exec, s[6:7]
	s_cbranch_execz .LBB0_223
	s_waitcnt lgkmcnt(0)
	v_mov_b32_e32 v0, 0x2000
	global_load_dword v0, v0, s[4:5] offset:1024 sc1
	s_add_u32 s12, s4, 0x2400
	s_addc_u32 s13, s5, 0
	s_waitcnt vmcnt(0)
	v_cmp_eq_u32_e32 vcc, v0, v1
	s_and_saveexec_b64 s[8:9], vcc
	s_cbranch_execz .LBB0_222
	s_add_u32 s10, s40, 0x4200
	s_addc_u32 s11, s41, 0
	s_mov_b32 s48, 1
	s_mov_b64 s[24:25], 0
	v_mov_b32_e32 v0, 0
	s_branch .LBB0_213

.LBB0_289:
	s_or_b64 exec, exec, s[8:9]
	v_cvt_f32_u32_e32 v4, v2
	s_waitcnt vmcnt(0)
	buffer_inv sc1
	v_readfirstlane_b32 s6, v3
	v_sub_u32_e32 v3, 0, v2
	v_rcp_iflag_f32_e32 v4, v4
	v_add_u32_e32 v5, s6, v1
	v_mul_f32_e32 v4, 0x4f7ffffe, v4
	v_cvt_u32_f32_e32 v4, v4
	v_mul_lo_u32 v1, v3, v4
	v_mul_hi_u32 v1, v4, v1
	v_add_u32_e32 v1, v4, v1
	v_mul_hi_u32 v1, v5, v1
	v_mul_lo_u32 v3, v1, v2
	v_sub_u32_e32 v3, v5, v3
	v_add_u32_e32 v4, 1, v1
	v_cmp_ge_u32_e32 vcc, v3, v2
	s_nop 1
	v_cndmask_b32_e32 v1, v1, v4, vcc
	v_sub_u32_e32 v4, v3, v2
	v_cndmask_b32_e32 v3, v3, v4, vcc
	v_add_u32_e32 v4, 1, v1
	v_cmp_ge_u32_e32 vcc, v3, v2
	v_add_u32_e32 v3, 1, v5
	s_nop 0
	v_cndmask_b32_e32 v1, v1, v4, vcc
	v_mul_lo_u32 v4, v2, v1
	v_add_u32_e32 v2, v4, v2
	v_cmp_ne_u32_e32 vcc, v3, v2
	s_and_saveexec_b64 s[6:7], vcc
	s_xor_b64 s[6:7], exec, s[6:7]
	s_cbranch_execz .LBB0_303
	s_waitcnt lgkmcnt(0)
	v_mov_b32_e32 v0, 0x2000
	global_load_dword v0, v0, s[4:5] offset:1024 sc1
	s_add_u32 s30, s4, 0x2400
	s_addc_u32 s31, s5, 0
	s_waitcnt vmcnt(0)
	v_cmp_eq_u32_e32 vcc, v0, v1
	s_and_saveexec_b64 s[8:9], vcc
	s_cbranch_execz .LBB0_302
	s_add_u32 s10, s40, 0x4200
	s_addc_u32 s11, s41, 0
	s_mov_b32 s54, 1
	s_mov_b64 s[36:37], 0
	v_mov_b32_e32 v0, 0
	s_branch .LBB0_293

.LBB0_344:
	s_or_b64 exec, exec, s[8:9]
	v_cvt_f32_u32_e32 v4, v2
	s_waitcnt vmcnt(0)
	buffer_inv sc1
	v_readfirstlane_b32 s6, v3
	v_sub_u32_e32 v3, 0, v2
	v_rcp_iflag_f32_e32 v4, v4
	v_add_u32_e32 v5, s6, v1
	v_mul_f32_e32 v4, 0x4f7ffffe, v4
	v_cvt_u32_f32_e32 v4, v4
	v_mul_lo_u32 v1, v3, v4
	v_mul_hi_u32 v1, v4, v1
	v_add_u32_e32 v1, v4, v1
	v_mul_hi_u32 v1, v5, v1
	v_mul_lo_u32 v3, v1, v2
	v_sub_u32_e32 v3, v5, v3
	v_add_u32_e32 v4, 1, v1
	v_cmp_ge_u32_e32 vcc, v3, v2
	s_nop 1
	v_cndmask_b32_e32 v1, v1, v4, vcc
	v_sub_u32_e32 v4, v3, v2
	v_cndmask_b32_e32 v3, v3, v4, vcc
	v_add_u32_e32 v4, 1, v1
	v_cmp_ge_u32_e32 vcc, v3, v2
	v_add_u32_e32 v3, 1, v5
	s_nop 0
	v_cndmask_b32_e32 v1, v1, v4, vcc
	v_mul_lo_u32 v4, v2, v1
	v_add_u32_e32 v2, v4, v2
	v_cmp_ne_u32_e32 vcc, v3, v2
	s_and_saveexec_b64 s[6:7], vcc
	s_xor_b64 s[6:7], exec, s[6:7]
	s_cbranch_execz .LBB0_358
	s_waitcnt lgkmcnt(0)
	v_mov_b32_e32 v0, 0x2000
	global_load_dword v0, v0, s[4:5] offset:1024 sc1
	s_add_u32 s16, s4, 0x2400
	s_addc_u32 s17, s5, 0
	s_waitcnt vmcnt(0)
	v_cmp_eq_u32_e32 vcc, v0, v1
	s_and_saveexec_b64 s[8:9], vcc
	s_cbranch_execz .LBB0_357
	s_add_u32 s10, s40, 0x4200
	s_addc_u32 s11, s41, 0
	s_mov_b32 s54, 1
	s_mov_b64 s[36:37], 0
	v_mov_b32_e32 v0, 0
	s_branch .LBB0_348

.LBB0_481:
	s_or_b64 exec, exec, s[16:17]
	v_cvt_f32_u32_e32 v4, v2
	s_waitcnt vmcnt(0)
	buffer_inv sc1
	v_readfirstlane_b32 s6, v3
	v_sub_u32_e32 v3, 0, v2
	v_rcp_iflag_f32_e32 v4, v4
	v_add_u32_e32 v5, s6, v1
	v_mul_f32_e32 v4, 0x4f7ffffe, v4
	v_cvt_u32_f32_e32 v4, v4
	v_mul_lo_u32 v1, v3, v4
	v_mul_hi_u32 v1, v4, v1
	v_add_u32_e32 v1, v4, v1
	v_mul_hi_u32 v1, v5, v1
	v_mul_lo_u32 v3, v1, v2
	v_sub_u32_e32 v3, v5, v3
	v_add_u32_e32 v4, 1, v1
	v_cmp_ge_u32_e32 vcc, v3, v2
	s_nop 1
	v_cndmask_b32_e32 v1, v1, v4, vcc
	v_sub_u32_e32 v4, v3, v2
	v_cndmask_b32_e32 v3, v3, v4, vcc
	v_add_u32_e32 v4, 1, v1
	v_cmp_ge_u32_e32 vcc, v3, v2
	v_add_u32_e32 v3, 1, v5
	s_nop 0
	v_cndmask_b32_e32 v1, v1, v4, vcc
	v_mul_lo_u32 v4, v2, v1
	v_add_u32_e32 v2, v4, v2
	v_cmp_ne_u32_e32 vcc, v3, v2
	s_and_saveexec_b64 s[6:7], vcc
	s_xor_b64 s[6:7], exec, s[6:7]
	s_cbranch_execz .LBB0_495
	s_waitcnt lgkmcnt(0)
	v_mov_b32_e32 v0, 0x2000
	global_load_dword v0, v0, s[4:5] offset:1024 sc1
	s_add_u32 s44, s4, 0x2400
	s_addc_u32 s45, s5, 0
	s_waitcnt vmcnt(0)
	v_cmp_eq_u32_e32 vcc, v0, v1
	s_and_saveexec_b64 s[16:17], vcc
	s_cbranch_execz .LBB0_494
	s_add_u32 s36, s40, 0x4200
	s_addc_u32 s37, s41, 0
	s_mov_b32 s58, 1
	s_mov_b64 s[46:47], 0
	v_mov_b32_e32 v0, 0
	s_branch .LBB0_485

.LBB0_626:
	s_or_b64 exec, exec, s[10:11]
	v_cvt_f32_u32_e32 v4, v2
	s_waitcnt vmcnt(0)
	buffer_inv sc1
	v_readfirstlane_b32 s8, v3
	v_sub_u32_e32 v3, 0, v2
	v_rcp_iflag_f32_e32 v4, v4
	v_add_u32_e32 v5, s8, v1
	v_mul_f32_e32 v4, 0x4f7ffffe, v4
	v_cvt_u32_f32_e32 v4, v4
	v_mul_lo_u32 v1, v3, v4
	v_mul_hi_u32 v1, v4, v1
	v_add_u32_e32 v1, v4, v1
	v_mul_hi_u32 v1, v5, v1
	v_mul_lo_u32 v3, v1, v2
	v_sub_u32_e32 v3, v5, v3
	v_add_u32_e32 v4, 1, v1
	v_cmp_ge_u32_e32 vcc, v3, v2
	s_nop 1
	v_cndmask_b32_e32 v1, v1, v4, vcc
	v_sub_u32_e32 v4, v3, v2
	v_cndmask_b32_e32 v3, v3, v4, vcc
	v_add_u32_e32 v4, 1, v1
	v_cmp_ge_u32_e32 vcc, v3, v2
	v_add_u32_e32 v3, 1, v5
	s_nop 0
	v_cndmask_b32_e32 v1, v1, v4, vcc
	v_mul_lo_u32 v4, v2, v1
	v_add_u32_e32 v2, v4, v2
	v_cmp_ne_u32_e32 vcc, v3, v2
	s_and_saveexec_b64 s[8:9], vcc
	s_xor_b64 s[8:9], exec, s[8:9]
	s_cbranch_execz .LBB0_640
	s_waitcnt lgkmcnt(0)
	v_mov_b32_e32 v0, 0x2000
	global_load_dword v0, v0, s[4:5] offset:1024 sc1
	s_add_u32 s16, s4, 0x2400
	s_addc_u32 s17, s5, 0
	s_waitcnt vmcnt(0)
	v_cmp_eq_u32_e32 vcc, v0, v1
	s_and_saveexec_b64 s[10:11], vcc
	s_cbranch_execz .LBB0_639
	s_add_u32 s12, s40, 0x4200
	s_addc_u32 s13, s41, 0
	s_mov_b32 s54, 1
	s_mov_b64 s[36:37], 0
	v_mov_b32_e32 v0, 0
	s_branch .LBB0_630

.LBB0_681:
	s_or_b64 exec, exec, s[12:13]
	v_cvt_f32_u32_e32 v4, v2
	s_waitcnt vmcnt(0)
	buffer_inv sc1
	v_readfirstlane_b32 s10, v3
	v_sub_u32_e32 v3, 0, v2
	v_rcp_iflag_f32_e32 v4, v4
	v_add_u32_e32 v5, s10, v1
	v_mul_f32_e32 v4, 0x4f7ffffe, v4
	v_cvt_u32_f32_e32 v4, v4
	v_mul_lo_u32 v1, v3, v4
	v_mul_hi_u32 v1, v4, v1
	v_add_u32_e32 v1, v4, v1
	v_mul_hi_u32 v1, v5, v1
	v_mul_lo_u32 v3, v1, v2
	v_sub_u32_e32 v3, v5, v3
	v_add_u32_e32 v4, 1, v1
	v_cmp_ge_u32_e32 vcc, v3, v2
	s_nop 1
	v_cndmask_b32_e32 v1, v1, v4, vcc
	v_sub_u32_e32 v4, v3, v2
	v_cndmask_b32_e32 v3, v3, v4, vcc
	v_add_u32_e32 v4, 1, v1
	v_cmp_ge_u32_e32 vcc, v3, v2
	v_add_u32_e32 v3, 1, v5
	s_nop 0
	v_cndmask_b32_e32 v1, v1, v4, vcc
	v_mul_lo_u32 v4, v2, v1
	v_add_u32_e32 v2, v4, v2
	v_cmp_ne_u32_e32 vcc, v3, v2
	s_and_saveexec_b64 s[10:11], vcc
	s_xor_b64 s[10:11], exec, s[10:11]
	s_cbranch_execz .LBB0_695
	s_waitcnt lgkmcnt(0)
	v_mov_b32_e32 v0, 0x2000
	global_load_dword v0, v0, s[8:9] offset:1024 sc1
	s_add_u32 s30, s8, 0x2400
	s_addc_u32 s31, s9, 0
	s_waitcnt vmcnt(0)
	v_cmp_eq_u32_e32 vcc, v0, v1
	s_and_saveexec_b64 s[12:13], vcc
	s_cbranch_execz .LBB0_694
	s_add_u32 s16, s40, 0x4200
	s_addc_u32 s17, s41, 0
	s_mov_b32 s54, 1
	s_mov_b64 s[36:37], 0
	v_mov_b32_e32 v0, 0
	s_branch .LBB0_685

.LBB0_749:
	s_or_b64 exec, exec, s[16:17]
	v_cvt_f32_u32_e32 v4, v2
	s_waitcnt vmcnt(0)
	buffer_inv sc1
	v_readfirstlane_b32 s12, v3
	v_sub_u32_e32 v3, 0, v2
	v_rcp_iflag_f32_e32 v4, v4
	v_add_u32_e32 v5, s12, v1
	v_mul_f32_e32 v4, 0x4f7ffffe, v4
	v_cvt_u32_f32_e32 v4, v4
	v_mul_lo_u32 v1, v3, v4
	v_mul_hi_u32 v1, v4, v1
	v_add_u32_e32 v1, v4, v1
	v_mul_hi_u32 v1, v5, v1
	v_mul_lo_u32 v3, v1, v2
	v_sub_u32_e32 v3, v5, v3
	v_add_u32_e32 v4, 1, v1
	v_cmp_ge_u32_e32 vcc, v3, v2
	s_nop 1
	v_cndmask_b32_e32 v1, v1, v4, vcc
	v_sub_u32_e32 v4, v3, v2
	v_cndmask_b32_e32 v3, v3, v4, vcc
	v_add_u32_e32 v4, 1, v1
	v_cmp_ge_u32_e32 vcc, v3, v2
	v_add_u32_e32 v3, 1, v5
	s_nop 0
	v_cndmask_b32_e32 v1, v1, v4, vcc
	v_mul_lo_u32 v4, v2, v1
	v_add_u32_e32 v2, v4, v2
	v_cmp_ne_u32_e32 vcc, v3, v2
	s_and_saveexec_b64 s[12:13], vcc
	s_xor_b64 s[12:13], exec, s[12:13]
	s_cbranch_execz .LBB0_763
	s_waitcnt lgkmcnt(0)
	v_mov_b32_e32 v0, 0x2000
	global_load_dword v0, v0, s[10:11] offset:1024 sc1
	s_add_u32 s30, s10, 0x2400
	s_addc_u32 s31, s11, 0
	s_waitcnt vmcnt(0)
	v_cmp_eq_u32_e32 vcc, v0, v1
	s_and_saveexec_b64 s[16:17], vcc
	s_cbranch_execz .LBB0_762
	s_add_u32 s18, s40, 0x4200
	s_addc_u32 s19, s41, 0
	s_mov_b32 s54, 1
	s_mov_b64 s[36:37], 0
	v_mov_b32_e32 v0, 0
	s_branch .LBB0_753

.LBB0_976:
	s_or_b64 exec, exec, s[16:17]
	v_cvt_f32_u32_e32 v4, v2
	s_waitcnt vmcnt(0)
	buffer_inv sc1
	v_readfirstlane_b32 s12, v3
	v_sub_u32_e32 v3, 0, v2
	v_rcp_iflag_f32_e32 v4, v4
	v_add_u32_e32 v5, s12, v1
	v_mul_f32_e32 v4, 0x4f7ffffe, v4
	v_cvt_u32_f32_e32 v4, v4
	v_mul_lo_u32 v1, v3, v4
	v_mul_hi_u32 v1, v4, v1
	v_add_u32_e32 v1, v4, v1
	v_mul_hi_u32 v1, v5, v1
	v_mul_lo_u32 v3, v1, v2
	v_sub_u32_e32 v3, v5, v3
	v_add_u32_e32 v4, 1, v1
	v_cmp_ge_u32_e32 vcc, v3, v2
	s_nop 1
	v_cndmask_b32_e32 v1, v1, v4, vcc
	v_sub_u32_e32 v4, v3, v2
	v_cndmask_b32_e32 v3, v3, v4, vcc
	v_add_u32_e32 v4, 1, v1
	v_cmp_ge_u32_e32 vcc, v3, v2
	v_add_u32_e32 v3, 1, v5
	s_nop 0
	v_cndmask_b32_e32 v1, v1, v4, vcc
	v_mul_lo_u32 v4, v2, v1
	v_add_u32_e32 v2, v4, v2
	v_cmp_ne_u32_e32 vcc, v3, v2
	s_and_saveexec_b64 s[12:13], vcc
	s_xor_b64 s[12:13], exec, s[12:13]
	s_cbranch_execz .LBB0_990
	s_waitcnt lgkmcnt(0)
	v_mov_b32_e32 v0, 0x2000
	global_load_dword v0, v0, s[10:11] offset:1024 sc1
	s_add_u32 s36, s10, 0x2400
	s_addc_u32 s37, s11, 0
	s_waitcnt vmcnt(0)
	v_cmp_eq_u32_e32 vcc, v0, v1
	s_and_saveexec_b64 s[16:17], vcc
	s_cbranch_execz .LBB0_989
	s_add_u32 s18, s40, 0x4200
	s_addc_u32 s19, s41, 0
	s_mov_b32 s56, 1
	s_mov_b64 s[44:45], 0
	v_mov_b32_e32 v0, 0
	s_branch .LBB0_980

.LBB0_1260:
	s_or_b64 exec, exec, s[16:17]
	v_cvt_f32_u32_e32 v4, v2
	s_waitcnt vmcnt(0)
	buffer_inv sc1
	v_readfirstlane_b32 s12, v3
	v_sub_u32_e32 v3, 0, v2
	v_rcp_iflag_f32_e32 v4, v4
	v_add_u32_e32 v5, s12, v1
	v_mul_f32_e32 v4, 0x4f7ffffe, v4
	v_cvt_u32_f32_e32 v4, v4
	v_mul_lo_u32 v1, v3, v4
	v_mul_hi_u32 v1, v4, v1
	v_add_u32_e32 v1, v4, v1
	v_mul_hi_u32 v1, v5, v1
	v_mul_lo_u32 v3, v1, v2
	v_sub_u32_e32 v3, v5, v3
	v_add_u32_e32 v4, 1, v1
	v_cmp_ge_u32_e32 vcc, v3, v2
	s_nop 1
	v_cndmask_b32_e32 v1, v1, v4, vcc
	v_sub_u32_e32 v4, v3, v2
	v_cndmask_b32_e32 v3, v3, v4, vcc
	v_add_u32_e32 v4, 1, v1
	v_cmp_ge_u32_e32 vcc, v3, v2
	v_add_u32_e32 v3, 1, v5
	s_nop 0
	v_cndmask_b32_e32 v1, v1, v4, vcc
	v_mul_lo_u32 v4, v2, v1
	v_add_u32_e32 v2, v4, v2
	v_cmp_ne_u32_e32 vcc, v3, v2
	s_and_saveexec_b64 s[12:13], vcc
	s_xor_b64 s[12:13], exec, s[12:13]
	s_cbranch_execz .LBB0_1274
	s_waitcnt lgkmcnt(0)
	v_mov_b32_e32 v0, 0x2000
	global_load_dword v0, v0, s[10:11] offset:1024 sc1
	s_add_u32 s30, s10, 0x2400
	s_addc_u32 s31, s11, 0
	s_waitcnt vmcnt(0)
	v_cmp_eq_u32_e32 vcc, v0, v1
	s_and_saveexec_b64 s[16:17], vcc
	s_cbranch_execz .LBB0_1273
	s_add_u32 s18, s40, 0x4200
	s_addc_u32 s19, s41, 0
	s_mov_b32 s52, 1
	s_mov_b64 s[36:37], 0
	v_mov_b32_e32 v0, 0
	s_branch .LBB0_1264

.LBB0_1459:
	s_or_b64 exec, exec, s[12:13]
	v_cvt_f32_u32_e32 v4, v2
	s_waitcnt vmcnt(0)
	buffer_inv sc1
	v_readfirstlane_b32 s10, v3
	v_sub_u32_e32 v3, 0, v2
	v_rcp_iflag_f32_e32 v4, v4
	v_add_u32_e32 v5, s10, v1
	v_mul_f32_e32 v4, 0x4f7ffffe, v4
	v_cvt_u32_f32_e32 v4, v4
	v_mul_lo_u32 v1, v3, v4
	v_mul_hi_u32 v1, v4, v1
	v_add_u32_e32 v1, v4, v1
	v_mul_hi_u32 v1, v5, v1
	v_mul_lo_u32 v3, v1, v2
	v_sub_u32_e32 v3, v5, v3
	v_add_u32_e32 v4, 1, v1
	v_cmp_ge_u32_e32 vcc, v3, v2
	s_nop 1
	v_cndmask_b32_e32 v1, v1, v4, vcc
	v_sub_u32_e32 v4, v3, v2
	v_cndmask_b32_e32 v3, v3, v4, vcc
	v_add_u32_e32 v4, 1, v1
	v_cmp_ge_u32_e32 vcc, v3, v2
	v_add_u32_e32 v3, 1, v5
	s_nop 0
	v_cndmask_b32_e32 v1, v1, v4, vcc
	v_mul_lo_u32 v4, v2, v1
	v_add_u32_e32 v2, v4, v2
	v_cmp_ne_u32_e32 vcc, v3, v2
	s_and_saveexec_b64 s[10:11], vcc
	s_xor_b64 s[10:11], exec, s[10:11]
	s_cbranch_execz .LBB0_1473
	s_waitcnt lgkmcnt(0)
	v_mov_b32_e32 v0, 0x2000
	global_load_dword v0, v0, s[8:9] offset:1024 sc1
	s_add_u32 s18, s8, 0x2400
	s_addc_u32 s19, s9, 0
	s_waitcnt vmcnt(0)
	v_cmp_eq_u32_e32 vcc, v0, v1
	s_and_saveexec_b64 s[12:13], vcc
	s_cbranch_execz .LBB0_1472
	s_add_u32 s16, s40, 0x4200
	s_addc_u32 s17, s41, 0
	s_mov_b32 s50, 1
	s_mov_b64 s[30:31], 0
	v_mov_b32_e32 v0, 0
	s_branch .LBB0_1463

.LBB0_1539:
	s_or_b64 exec, exec, s[8:9]
	v_cvt_f32_u32_e32 v4, v2
	s_waitcnt vmcnt(0)
	buffer_inv sc1
	v_readfirstlane_b32 s6, v3
	v_sub_u32_e32 v3, 0, v2
	v_rcp_iflag_f32_e32 v4, v4
	v_add_u32_e32 v5, s6, v1
	v_mul_f32_e32 v4, 0x4f7ffffe, v4
	v_cvt_u32_f32_e32 v4, v4
	v_mul_lo_u32 v1, v3, v4
	v_mul_hi_u32 v1, v4, v1
	v_add_u32_e32 v1, v4, v1
	v_mul_hi_u32 v1, v5, v1
	v_mul_lo_u32 v3, v1, v2
	v_sub_u32_e32 v3, v5, v3
	v_add_u32_e32 v4, 1, v1
	v_cmp_ge_u32_e32 vcc, v3, v2
	s_nop 1
	v_cndmask_b32_e32 v1, v1, v4, vcc
	v_sub_u32_e32 v4, v3, v2
	v_cndmask_b32_e32 v3, v3, v4, vcc
	v_add_u32_e32 v4, 1, v1
	v_cmp_ge_u32_e32 vcc, v3, v2
	v_add_u32_e32 v3, 1, v5
	s_nop 0
	v_cndmask_b32_e32 v1, v1, v4, vcc
	v_mul_lo_u32 v4, v2, v1
	v_add_u32_e32 v2, v4, v2
	v_cmp_ne_u32_e32 vcc, v3, v2
	s_and_saveexec_b64 s[6:7], vcc
	s_xor_b64 s[6:7], exec, s[6:7]
	s_cbranch_execz .LBB0_1553
	s_waitcnt lgkmcnt(0)
	v_mov_b32_e32 v0, 0x2000
	global_load_dword v0, v0, s[2:3] offset:1024 sc1
	s_add_u32 s12, s2, 0x2400
	s_addc_u32 s13, s3, 0
	s_waitcnt vmcnt(0)
	v_cmp_eq_u32_e32 vcc, v0, v1
	s_and_saveexec_b64 s[8:9], vcc
	s_cbranch_execz .LBB0_1552
	s_add_u32 s10, s40, 0x4200
	s_addc_u32 s11, s41, 0
	s_mov_b32 s24, 1
	s_mov_b64 s[14:15], 0
	v_mov_b32_e32 v0, 0
	s_branch .LBB0_1543
